# in-proj A K-loop: store-trickle bookkeeping takes a 2-instruction fast path at every wait site outside the trickle iterations (parked count armed when the loop counter reaches T); on top of v98
# baseline (speedup 1.0000x reference)
; #define PG8_STAGE(bufoff, gbase, voff) do { _Pragma("unroll") for (int _i = 0; _i < 2; ++_i) \
;         __builtin_amdgcn_global_load_lds((const unsigned*)((const char*)(gbase) + (voff)[_i]), (PG8_LAS unsigned*)(lds + (bufoff) + ldsw + _i * 8192), 16, 0, 0); } while (0)
; #define PG8_LDA(dst, b, h) do { _Pragma("unroll") for (int m = 0; m < 4; ++m) _Pragma("unroll") for (int k = 0; k < 2; ++k) dst[m][k] = *(const PG8_LAS bf16x8*)(lds + PG8_SA(b, h) + aoff + m * 2048 + k * 1024); } while (0)
; #define PG8_LDB(dst, b, h) do { _Pragma("unroll") for (int n = 0; n < 2; ++n) _Pragma("unroll") for (int k = 0; k < 2; ++k) dst[n][k] = *(const PG8_LAS bf16x8*)(lds + PG8_SB(b, h) + boff + n * 2048 + k * 1024); } while (0)
; #define PG8_WAIT_V(n) asm volatile("s_waitcnt vmcnt(" #n ")" ::: "memory")
; #define PG8_WAIT_L(n) asm volatile("s_waitcnt lgkmcnt(" #n ")" ::: "memory")
; #define PG8_BAR __builtin_amdgcn_s_barrier()
; #define PG8_SCHED __builtin_amdgcn_sched_barrier(0)
;     ...
;         const bool has_next = S.next(ui + 1, nxt);
;         const char* nA = has_next ? (const char*)g.A + (size_t)nxt.pm * tstep : cA; const char* nB = has_next ? (const char*)g.Bt + (size_t)nxt.pn * tstep : cB;
;         for (int t = 0; t < nt; t += 2) {
;             const bool last = (t == nt - 2);
;             const char* a1 = cA + (size_t)(t + 1) * kstep;
;             const char* a2 = last ? nA : cA + (size_t)(t + 2) * kstep; const char* b2 = last ? nB : cB + (size_t)(t + 2) * kstep;
;             const char* a3 = a2 + kstep; const char* b3 = b2 + kstep;
;             PG8_LDB(B0, 0, 0); PG8_LDB(B1, 0, 1); PG8_SCHED; PG8_LDA(At, 0, 0); PG8_STAGE(PG8_SA(1, 1), a1 + hstep, voffA);
;             PG8_WAIT_V(8); PG8_WAIT_L(0); PG8_BAR; PG8_MMA(0, 0, At, B0); PG8_MMA(0, 1, At, B1); PG8_BAR; PG8_SCHED;
.Lpka_nomove:
	s_mov_b32 s100, 0
	s_mov_b32 s32, s101
	s_mov_b32 s101, 0
.LBB0_206:
	s_add_u32 s72, s38, 0xfffc0080
	s_addc_u32 s73, s39, -1
	s_add_i32 s82, 0, 0x10000
	s_cmp_eq_u32 s81, 12
	s_cselect_b32 s77, s2, s73
	s_cselect_b32 s76, s31, s72
	s_cselect_b32 s73, s29, s80
	s_cselect_b32 s72, s60, s61
	s_add_i32 s86, 0, 0x14000
	s_waitcnt lgkmcnt(0)
	v_add_u32_e32 v156, s82, v195
	v_add_u32_e32 v183, s86, v195
	ds_read_b128 v[144:147], v156
	ds_read_b128 v[148:151], v156 offset:1024
	ds_read_b128 v[152:155], v156 offset:2048
	ds_read_b128 v[156:159], v156 offset:3072
	ds_read_b128 v[186:189], v183
	ds_read_b128 v[198:201], v183 offset:1024
	ds_read_b128 v[202:205], v183 offset:2048
	ds_read_b128 v[206:209], v183 offset:3072
	s_add_i32 m0, s63, 0xc000
	ds_read_b128 v[210:213], v197
	ds_read_b128 v[214:217], v197 offset:1024
	ds_read_b128 v[218:221], v197 offset:2048
	ds_read_b128 v[222:225], v197 offset:3072
	ds_read_b128 v[226:229], v197 offset:4096
	ds_read_b128 v[230:233], v197 offset:5120
	ds_read_b128 v[234:237], v197 offset:6144
	ds_read_b128 v[238:241], v197 offset:7168
	global_load_lds_dwordx4 v178, s[38:39]
	s_add_i32 m0, s63, 0xe000
	s_nop 0
	global_load_lds_dwordx4 v180, s[38:39]
	s_cmp_eq_u64 s[100:101], 0
	s_cbranch_scc1 .Lpka_w8a
	s_lshl_b32 s100, s100, 1
	s_and_b32 s100, s100, 6
	s_cmp_eq_u32 s101, 0
	s_cbranch_scc1 .Lpka_na
	s_cmp_lt_i32 s81, 2
	s_cbranch_scc1 .Lpka_na
	s_or_b32 s100, s100, 1
	s_cmp_eq_u32 s101, 8
	s_cbranch_scc1 .Lpka_s0a
	s_cmp_eq_u32 s101, 7
	s_cbranch_scc1 .Lpka_s1a
	s_cmp_eq_u32 s101, 6
	s_cbranch_scc1 .Lpka_s2a
	s_cmp_eq_u32 s101, 5
	s_cbranch_scc1 .Lpka_s3a
	s_cmp_eq_u32 s101, 4
	s_cbranch_scc1 .Lpka_s4a
	s_cmp_eq_u32 s101, 3
	s_cbranch_scc1 .Lpka_s5a
	s_cmp_eq_u32 s101, 2
	s_cbranch_scc1 .Lpka_s6a
	global_store_dwordx4 v[254:255], v[12:15], off offset:64
	s_branch .Lpka_ia

; #define PG8_STAGE(bufoff, gbase, voff) do { _Pragma("unroll") for (int _i = 0; _i < 2; ++_i) \
;         __builtin_amdgcn_global_load_lds((const unsigned*)((const char*)(gbase) + (voff)[_i]), (PG8_LAS unsigned*)(lds + (bufoff) + ldsw + _i * 8192), 16, 0, 0); } while (0)
; #define PG8_LDA(dst, b, h) do { _Pragma("unroll") for (int m = 0; m < 4; ++m) _Pragma("unroll") for (int k = 0; k < 2; ++k) dst[m][k] = *(const PG8_LAS bf16x8*)(lds + PG8_SA(b, h) + aoff + m * 2048 + k * 1024); } while (0)
; #define PG8_WAIT_V(n) asm volatile("s_waitcnt vmcnt(" #n ")" ::: "memory")
; #define PG8_WAIT_L(n) asm volatile("s_waitcnt lgkmcnt(" #n ")" ::: "memory")
; #define PG8_BAR __builtin_amdgcn_s_barrier()
; #define PG8_SCHED __builtin_amdgcn_sched_barrier(0)
;     ...
;             PG8_WAIT_V(8); PG8_WAIT_L(0); PG8_BAR; PG8_MMA(0, 0, At, B0); PG8_MMA(0, 1, At, B1); PG8_BAR; PG8_SCHED;
;             PG8_LDA(At, 0, 1); PG8_STAGE(PG8_SB(0, 0), b2, voffB); PG8_STAGE(PG8_SB(0, 1), b2 + hstepB, voffB); PG8_STAGE(PG8_SA(0, 0), a2, voffA);
;             PG8_WAIT_V(8); PG8_WAIT_L(0); PG8_BAR; PG8_MMA(1, 0, At, B0); PG8_MMA(1, 1, At, B1); PG8_BAR; PG8_SCHED;
.Lpka_da:
	s_waitcnt lgkmcnt(0)
	s_barrier
	v_mfma_f32_16x16x32_bf16 v[132:135], v[144:147], v[210:213], v[132:135]
	v_mfma_f32_16x16x32_bf16 v[128:131], v[152:155], v[210:213], v[128:131]
	v_mfma_f32_16x16x32_bf16 v[116:119], v[144:147], v[218:221], v[116:119]
	v_mfma_f32_16x16x32_bf16 v[112:115], v[152:155], v[218:221], v[112:115]
	v_mfma_f32_16x16x32_bf16 v[100:103], v[144:147], v[226:229], v[100:103]
	v_mfma_f32_16x16x32_bf16 v[96:99], v[152:155], v[226:229], v[96:99]
	v_mfma_f32_16x16x32_bf16 v[84:87], v[144:147], v[234:237], v[84:87]
	v_mfma_f32_16x16x32_bf16 v[80:83], v[152:155], v[234:237], v[80:83]
	v_mfma_f32_16x16x32_bf16 v[132:135], v[148:151], v[214:217], v[132:135]
	v_mfma_f32_16x16x32_bf16 v[128:131], v[156:159], v[214:217], v[128:131]
	v_mfma_f32_16x16x32_bf16 v[116:119], v[148:151], v[222:225], v[116:119]
	v_mfma_f32_16x16x32_bf16 v[112:115], v[156:159], v[222:225], v[112:115]
	v_mfma_f32_16x16x32_bf16 v[100:103], v[148:151], v[230:233], v[100:103]
	v_mfma_f32_16x16x32_bf16 v[96:99], v[156:159], v[230:233], v[96:99]
	v_mfma_f32_16x16x32_bf16 v[84:87], v[148:151], v[238:241], v[84:87]
	v_mfma_f32_16x16x32_bf16 v[80:83], v[156:159], v[238:241], v[80:83]
	v_mfma_f32_16x16x32_bf16 v[140:143], v[186:189], v[210:213], v[140:143]
	v_mfma_f32_16x16x32_bf16 v[136:139], v[202:205], v[210:213], v[136:139]
	v_mfma_f32_16x16x32_bf16 v[124:127], v[186:189], v[218:221], v[124:127]
	v_mfma_f32_16x16x32_bf16 v[120:123], v[202:205], v[218:221], v[120:123]
	v_mfma_f32_16x16x32_bf16 v[108:111], v[186:189], v[226:229], v[108:111]
	v_mfma_f32_16x16x32_bf16 v[104:107], v[202:205], v[226:229], v[104:107]
	v_mfma_f32_16x16x32_bf16 v[92:95], v[186:189], v[234:237], v[92:95]
	v_mfma_f32_16x16x32_bf16 v[88:91], v[202:205], v[234:237], v[88:91]
	v_mfma_f32_16x16x32_bf16 v[140:143], v[198:201], v[214:217], v[140:143]
	v_mfma_f32_16x16x32_bf16 v[136:139], v[206:209], v[214:217], v[136:139]
	v_mfma_f32_16x16x32_bf16 v[124:127], v[198:201], v[222:225], v[124:127]
	v_mfma_f32_16x16x32_bf16 v[120:123], v[206:209], v[222:225], v[120:123]
	v_mfma_f32_16x16x32_bf16 v[108:111], v[198:201], v[230:233], v[108:111]
	v_mfma_f32_16x16x32_bf16 v[104:107], v[206:209], v[230:233], v[104:107]
	v_mfma_f32_16x16x32_bf16 v[92:95], v[198:201], v[238:241], v[92:95]
	v_mfma_f32_16x16x32_bf16 v[88:91], v[206:209], v[238:241], v[88:91]
	s_barrier
	s_add_i32 s82, s82, s15
	s_mov_b32 m0, s82
	ds_read_b128 v[210:213], v197 offset:16384
	ds_read_b128 v[214:217], v197 offset:17408
	ds_read_b128 v[218:221], v197 offset:18432
	ds_read_b128 v[222:225], v197 offset:19456
	ds_read_b128 v[226:229], v197 offset:20480
	ds_read_b128 v[230:233], v197 offset:21504
	ds_read_b128 v[234:237], v197 offset:22528
	ds_read_b128 v[238:241], v197 offset:23552
	global_load_lds_dwordx4 v170, s[72:73]
	s_add_i32 m0, s82, 0x2000
	s_add_u32 s82, s72, 0x10000
	s_addc_u32 s83, s73, 0
	s_add_i32 s86, s86, s15
	global_load_lds_dwordx4 v166, s[72:73]
	s_mov_b32 m0, s86
	s_nop 0
	global_load_lds_dwordx4 v170, s[82:83]
	s_add_i32 m0, s86, 0x2000
	s_nop 0
	global_load_lds_dwordx4 v166, s[82:83]
	s_mov_b32 m0, s63
	s_nop 0
	global_load_lds_dwordx4 v172, s[76:77]
	s_mov_b32 m0, s64
	s_nop 0
	global_load_lds_dwordx4 v168, s[76:77]
	s_cmp_eq_u64 s[100:101], 0
	s_cbranch_scc1 .Lpka_w8b
	s_lshl_b32 s100, s100, 1
	s_and_b32 s100, s100, 6
	s_bcnt1_i32_b32 vcc_lo, s100
	s_cmp_eq_u32 vcc_lo, 0
	s_cbranch_scc1 .Lpka_w8b
	s_cmp_eq_u32 vcc_lo, 1
	s_cbranch_scc1 .Lpka_w9b
	s_waitcnt vmcnt(10)
	s_branch .Lpka_db

; #define PG8_STAGE(bufoff, gbase, voff) do { _Pragma("unroll") for (int _i = 0; _i < 2; ++_i) \
;         __builtin_amdgcn_global_load_lds((const unsigned*)((const char*)(gbase) + (voff)[_i]), (PG8_LAS unsigned*)(lds + (bufoff) + ldsw + _i * 8192), 16, 0, 0); } while (0)
; #define PG8_LDA(dst, b, h) do { _Pragma("unroll") for (int m = 0; m < 4; ++m) _Pragma("unroll") for (int k = 0; k < 2; ++k) dst[m][k] = *(const PG8_LAS bf16x8*)(lds + PG8_SA(b, h) + aoff + m * 2048 + k * 1024); } while (0)
; #define PG8_LDB(dst, b, h) do { _Pragma("unroll") for (int n = 0; n < 2; ++n) _Pragma("unroll") for (int k = 0; k < 2; ++k) dst[n][k] = *(const PG8_LAS bf16x8*)(lds + PG8_SB(b, h) + boff + n * 2048 + k * 1024); } while (0)
; #define PG8_WAIT_V(n) asm volatile("s_waitcnt vmcnt(" #n ")" ::: "memory")
; #define PG8_WAIT_L(n) asm volatile("s_waitcnt lgkmcnt(" #n ")" ::: "memory")
; #define PG8_BAR __builtin_amdgcn_s_barrier()
; #define PG8_SCHED __builtin_amdgcn_sched_barrier(0)
;     ...
;             PG8_WAIT_V(8); PG8_WAIT_L(0); PG8_BAR; PG8_MMA(1, 0, At, B0); PG8_MMA(1, 1, At, B1); PG8_BAR; PG8_SCHED;
;             PG8_LDB(B0, 1, 0); PG8_LDB(B1, 1, 1); PG8_SCHED; PG8_LDA(At, 1, 0); PG8_STAGE(PG8_SA(0, 1), a2 + hstep, voffA);
;             PG8_WAIT_V(8); PG8_WAIT_L(0); PG8_BAR; PG8_MMA(0, 0, At, B0); PG8_MMA(0, 1, At, B1); PG8_BAR; PG8_SCHED;
.Lpka_db:
	s_waitcnt lgkmcnt(0)
	s_barrier
	v_mfma_f32_16x16x32_bf16 v[68:71], v[144:147], v[210:213], v[68:71]
	v_mfma_f32_16x16x32_bf16 v[64:67], v[152:155], v[210:213], v[64:67]
	v_mfma_f32_16x16x32_bf16 v[52:55], v[144:147], v[218:221], v[52:55]
	v_mfma_f32_16x16x32_bf16 v[48:51], v[152:155], v[218:221], v[48:51]
	v_mfma_f32_16x16x32_bf16 v[36:39], v[144:147], v[226:229], v[36:39]
	v_mfma_f32_16x16x32_bf16 v[32:35], v[152:155], v[226:229], v[32:35]
	v_mfma_f32_16x16x32_bf16 v[20:23], v[144:147], v[234:237], v[20:23]
	v_mfma_f32_16x16x32_bf16 v[16:19], v[152:155], v[234:237], v[16:19]
	v_mfma_f32_16x16x32_bf16 v[68:71], v[148:151], v[214:217], v[68:71]
	v_mfma_f32_16x16x32_bf16 v[64:67], v[156:159], v[214:217], v[64:67]
	v_mfma_f32_16x16x32_bf16 v[52:55], v[148:151], v[222:225], v[52:55]
	v_mfma_f32_16x16x32_bf16 v[48:51], v[156:159], v[222:225], v[48:51]
	v_mfma_f32_16x16x32_bf16 v[36:39], v[148:151], v[230:233], v[36:39]
	v_mfma_f32_16x16x32_bf16 v[32:35], v[156:159], v[230:233], v[32:35]
	v_mfma_f32_16x16x32_bf16 v[20:23], v[148:151], v[238:241], v[20:23]
	v_mfma_f32_16x16x32_bf16 v[16:19], v[156:159], v[238:241], v[16:19]
	v_mfma_f32_16x16x32_bf16 v[76:79], v[186:189], v[210:213], v[76:79]
	v_mfma_f32_16x16x32_bf16 v[72:75], v[202:205], v[210:213], v[72:75]
	v_mfma_f32_16x16x32_bf16 v[60:63], v[186:189], v[218:221], v[60:63]
	v_mfma_f32_16x16x32_bf16 v[56:59], v[202:205], v[218:221], v[56:59]
	v_mfma_f32_16x16x32_bf16 v[44:47], v[186:189], v[226:229], v[44:47]
	v_mfma_f32_16x16x32_bf16 v[40:43], v[202:205], v[226:229], v[40:43]
	v_mfma_f32_16x16x32_bf16 v[24:27], v[186:189], v[234:237], v[24:27]
	v_mfma_f32_16x16x32_bf16 v[28:31], v[202:205], v[234:237], v[28:31]
	v_mfma_f32_16x16x32_bf16 v[76:79], v[198:201], v[214:217], v[76:79]
	v_mfma_f32_16x16x32_bf16 v[72:75], v[206:209], v[214:217], v[72:75]
	v_mfma_f32_16x16x32_bf16 v[60:63], v[198:201], v[222:225], v[60:63]
	v_mfma_f32_16x16x32_bf16 v[56:59], v[206:209], v[222:225], v[56:59]
	v_mfma_f32_16x16x32_bf16 v[44:47], v[198:201], v[230:233], v[44:47]
	v_mfma_f32_16x16x32_bf16 v[40:43], v[206:209], v[230:233], v[40:43]
	v_mfma_f32_16x16x32_bf16 v[24:27], v[198:201], v[238:241], v[24:27]
	v_mfma_f32_16x16x32_bf16 v[28:31], v[206:209], v[238:241], v[28:31]
	s_barrier
	s_add_i32 s82, 0, 0x18000
	s_add_i32 s83, 0, 0x1c000
	v_add_u32_e32 v156, s82, v195
	v_add_u32_e32 v183, s83, v195
	ds_read_b128 v[144:147], v156
	ds_read_b128 v[148:151], v156 offset:1024
	ds_read_b128 v[152:155], v156 offset:2048
	ds_read_b128 v[156:159], v156 offset:3072
	ds_read_b128 v[186:189], v183
	ds_read_b128 v[198:201], v183 offset:1024
	ds_read_b128 v[202:205], v183 offset:2048
	ds_read_b128 v[206:209], v183 offset:3072
	s_add_u32 s76, s76, 0x40000
	s_addc_u32 s77, s77, 0
	s_mov_b32 m0, s65
	ds_read_b128 v[210:213], v197 offset:32768
	ds_read_b128 v[214:217], v197 offset:33792
	ds_read_b128 v[218:221], v197 offset:34816
	ds_read_b128 v[222:225], v197 offset:35840
	ds_read_b128 v[226:229], v197 offset:36864
	ds_read_b128 v[230:233], v197 offset:37888
	ds_read_b128 v[234:237], v197 offset:38912
	ds_read_b128 v[238:241], v197 offset:39936
	global_load_lds_dwordx4 v172, s[76:77]
	s_mov_b32 m0, s66
	s_nop 0
	global_load_lds_dwordx4 v168, s[76:77]
	s_cmp_eq_u64 s[100:101], 0
	s_cbranch_scc1 .Lpka_w8c
	s_lshl_b32 s100, s100, 1
	s_and_b32 s100, s100, 6
	s_cmp_eq_u32 s101, 0
	s_cbranch_scc1 .Lpka_nc
	s_cmp_lt_i32 s81, 2
	s_cbranch_scc1 .Lpka_nc
	s_or_b32 s100, s100, 1
	s_cmp_eq_u32 s101, 8
	s_cbranch_scc1 .Lpka_s0c
	s_cmp_eq_u32 s101, 7
	s_cbranch_scc1 .Lpka_s1c
	s_cmp_eq_u32 s101, 6
	s_cbranch_scc1 .Lpka_s2c
	s_cmp_eq_u32 s101, 5
	s_cbranch_scc1 .Lpka_s3c
	s_cmp_eq_u32 s101, 4
	s_cbranch_scc1 .Lpka_s4c
	s_cmp_eq_u32 s101, 3
	s_cbranch_scc1 .Lpka_s5c
	s_cmp_eq_u32 s101, 2
	s_cbranch_scc1 .Lpka_s6c
	global_store_dwordx4 v[254:255], v[12:15], off offset:64
	s_branch .Lpka_ic

; #define PG8_STAGE(bufoff, gbase, voff) do { _Pragma("unroll") for (int _i = 0; _i < 2; ++_i) \
;         __builtin_amdgcn_global_load_lds((const unsigned*)((const char*)(gbase) + (voff)[_i]), (PG8_LAS unsigned*)(lds + (bufoff) + ldsw + _i * 8192), 16, 0, 0); } while (0)
; #define PG8_LDA(dst, b, h) do { _Pragma("unroll") for (int m = 0; m < 4; ++m) _Pragma("unroll") for (int k = 0; k < 2; ++k) dst[m][k] = *(const PG8_LAS bf16x8*)(lds + PG8_SA(b, h) + aoff + m * 2048 + k * 1024); } while (0)
; #define PG8_WAIT_V(n) asm volatile("s_waitcnt vmcnt(" #n ")" ::: "memory")
; #define PG8_WAIT_L(n) asm volatile("s_waitcnt lgkmcnt(" #n ")" ::: "memory")
; #define PG8_BAR __builtin_amdgcn_s_barrier()
; #define PG8_SCHED __builtin_amdgcn_sched_barrier(0)
;     ...
;             PG8_WAIT_V(8); PG8_WAIT_L(0); PG8_BAR; PG8_MMA(0, 0, At, B0); PG8_MMA(0, 1, At, B1); PG8_BAR; PG8_SCHED;
;             PG8_LDA(At, 1, 1); PG8_STAGE(PG8_SB(1, 0), b3, voffB); PG8_STAGE(PG8_SB(1, 1), b3 + hstepB, voffB); PG8_STAGE(PG8_SA(1, 0), a3, voffA);
;             PG8_WAIT_V(8); PG8_WAIT_L(0); PG8_BAR; PG8_MMA(1, 0, At, B0); PG8_MMA(1, 1, At, B1); PG8_BAR; PG8_SCHED;
.Lpka_dc:
	s_waitcnt lgkmcnt(0)
	s_barrier
	v_mfma_f32_16x16x32_bf16 v[132:135], v[144:147], v[210:213], v[132:135]
	v_mfma_f32_16x16x32_bf16 v[128:131], v[152:155], v[210:213], v[128:131]
	v_mfma_f32_16x16x32_bf16 v[116:119], v[144:147], v[218:221], v[116:119]
	v_mfma_f32_16x16x32_bf16 v[112:115], v[152:155], v[218:221], v[112:115]
	v_mfma_f32_16x16x32_bf16 v[100:103], v[144:147], v[226:229], v[100:103]
	v_mfma_f32_16x16x32_bf16 v[96:99], v[152:155], v[226:229], v[96:99]
	v_mfma_f32_16x16x32_bf16 v[84:87], v[144:147], v[234:237], v[84:87]
	v_mfma_f32_16x16x32_bf16 v[80:83], v[152:155], v[234:237], v[80:83]
	v_mfma_f32_16x16x32_bf16 v[132:135], v[148:151], v[214:217], v[132:135]
	v_mfma_f32_16x16x32_bf16 v[128:131], v[156:159], v[214:217], v[128:131]
	v_mfma_f32_16x16x32_bf16 v[116:119], v[148:151], v[222:225], v[116:119]
	v_mfma_f32_16x16x32_bf16 v[112:115], v[156:159], v[222:225], v[112:115]
	v_mfma_f32_16x16x32_bf16 v[100:103], v[148:151], v[230:233], v[100:103]
	v_mfma_f32_16x16x32_bf16 v[96:99], v[156:159], v[230:233], v[96:99]
	v_mfma_f32_16x16x32_bf16 v[84:87], v[148:151], v[238:241], v[84:87]
	v_mfma_f32_16x16x32_bf16 v[80:83], v[156:159], v[238:241], v[80:83]
	v_mfma_f32_16x16x32_bf16 v[140:143], v[186:189], v[210:213], v[140:143]
	v_mfma_f32_16x16x32_bf16 v[136:139], v[202:205], v[210:213], v[136:139]
	v_mfma_f32_16x16x32_bf16 v[124:127], v[186:189], v[218:221], v[124:127]
	v_mfma_f32_16x16x32_bf16 v[120:123], v[202:205], v[218:221], v[120:123]
	v_mfma_f32_16x16x32_bf16 v[108:111], v[186:189], v[226:229], v[108:111]
	v_mfma_f32_16x16x32_bf16 v[104:107], v[202:205], v[226:229], v[104:107]
	v_mfma_f32_16x16x32_bf16 v[92:95], v[186:189], v[234:237], v[92:95]
	v_mfma_f32_16x16x32_bf16 v[88:91], v[202:205], v[234:237], v[88:91]
	v_mfma_f32_16x16x32_bf16 v[140:143], v[198:201], v[214:217], v[140:143]
	v_mfma_f32_16x16x32_bf16 v[136:139], v[206:209], v[214:217], v[136:139]
	v_mfma_f32_16x16x32_bf16 v[124:127], v[198:201], v[222:225], v[124:127]
	v_mfma_f32_16x16x32_bf16 v[120:123], v[206:209], v[222:225], v[120:123]
	v_mfma_f32_16x16x32_bf16 v[108:111], v[198:201], v[230:233], v[108:111]
	v_mfma_f32_16x16x32_bf16 v[104:107], v[206:209], v[230:233], v[104:107]
	v_mfma_f32_16x16x32_bf16 v[92:95], v[198:201], v[238:241], v[92:95]
	v_mfma_f32_16x16x32_bf16 v[88:91], v[206:209], v[238:241], v[88:91]
	s_barrier
	s_add_i32 m0, s82, s15
	s_add_u32 vcc_lo, s72, 0x80
	s_addc_u32 vcc_hi, s73, 0
	ds_read_b128 v[210:213], v197 offset:49152
	ds_read_b128 v[214:217], v197 offset:50176
	ds_read_b128 v[218:221], v197 offset:51200
	ds_read_b128 v[222:225], v197 offset:52224
	ds_read_b128 v[226:229], v197 offset:53248
	ds_read_b128 v[230:233], v197 offset:54272
	ds_read_b128 v[234:237], v197 offset:55296
	ds_read_b128 v[238:241], v197 offset:56320
	global_load_lds_dwordx4 v170, vcc
	s_add_i32 m0, m0, 0x2000
	s_nop 0
	global_load_lds_dwordx4 v166, vcc
	s_add_u32 s72, s72, 0x10080
	s_addc_u32 s73, s73, 0
	s_add_i32 m0, s83, s15
	s_nop 0
	global_load_lds_dwordx4 v170, s[72:73]
	s_add_i32 m0, m0, 0x2000
	s_nop 0
	global_load_lds_dwordx4 v166, s[72:73]
	s_add_u32 vcc_lo, s76, 0xfffc0080
	s_addc_u32 vcc_hi, s77, -1
	s_mov_b32 m0, s74
	s_nop 0
	global_load_lds_dwordx4 v172, vcc
	s_mov_b32 m0, s75
	s_nop 0
	global_load_lds_dwordx4 v168, vcc
	s_cmp_eq_u64 s[100:101], 0
	s_cbranch_scc1 .Lpka_w8e
	s_lshl_b32 s100, s100, 1
	s_and_b32 s100, s100, 6
	s_bcnt1_i32_b32 vcc_lo, s100
	s_cmp_eq_u32 vcc_lo, 0
	s_cbranch_scc1 .Lpka_w8e
	s_cmp_eq_u32 vcc_lo, 1
	s_cbranch_scc1 .Lpka_w9e
	s_waitcnt vmcnt(10)
	s_branch .Lpka_de

; #define PG8_WAIT_V(n) asm volatile("s_waitcnt vmcnt(" #n ")" ::: "memory")
; #define PG8_WAIT_L(n) asm volatile("s_waitcnt lgkmcnt(" #n ")" ::: "memory")
; #define PG8_BAR __builtin_amdgcn_s_barrier()
; #define PG8_SCHED __builtin_amdgcn_sched_barrier(0)
;     ...
;             PG8_WAIT_V(8); PG8_WAIT_L(0); PG8_BAR; PG8_MMA(1, 0, At, B0); PG8_MMA(1, 1, At, B1); PG8_BAR; PG8_SCHED;
;         }
;         if constexpr (ALIGN_EPI) { if (wr == 0) PG8_BAR; }
.Lpka_de:
	s_waitcnt lgkmcnt(0)
	s_barrier
	v_mfma_f32_16x16x32_bf16 v[68:71], v[144:147], v[210:213], v[68:71]
	v_mfma_f32_16x16x32_bf16 v[64:67], v[152:155], v[210:213], v[64:67]
	v_mfma_f32_16x16x32_bf16 v[52:55], v[144:147], v[218:221], v[52:55]
	v_mfma_f32_16x16x32_bf16 v[48:51], v[152:155], v[218:221], v[48:51]
	v_mfma_f32_16x16x32_bf16 v[36:39], v[144:147], v[226:229], v[36:39]
	v_mfma_f32_16x16x32_bf16 v[32:35], v[152:155], v[226:229], v[32:35]
	v_mfma_f32_16x16x32_bf16 v[20:23], v[144:147], v[234:237], v[20:23]
	v_mfma_f32_16x16x32_bf16 v[16:19], v[152:155], v[234:237], v[16:19]
	v_mfma_f32_16x16x32_bf16 v[68:71], v[148:151], v[214:217], v[68:71]
	v_mfma_f32_16x16x32_bf16 v[64:67], v[156:159], v[214:217], v[64:67]
	v_mfma_f32_16x16x32_bf16 v[52:55], v[148:151], v[222:225], v[52:55]
	v_mfma_f32_16x16x32_bf16 v[48:51], v[156:159], v[222:225], v[48:51]
	v_mfma_f32_16x16x32_bf16 v[36:39], v[148:151], v[230:233], v[36:39]
	v_mfma_f32_16x16x32_bf16 v[32:35], v[156:159], v[230:233], v[32:35]
	v_mfma_f32_16x16x32_bf16 v[20:23], v[148:151], v[238:241], v[20:23]
	v_mfma_f32_16x16x32_bf16 v[16:19], v[156:159], v[238:241], v[16:19]
	v_mfma_f32_16x16x32_bf16 v[76:79], v[186:189], v[210:213], v[76:79]
	v_mfma_f32_16x16x32_bf16 v[72:75], v[202:205], v[210:213], v[72:75]
	v_mfma_f32_16x16x32_bf16 v[60:63], v[186:189], v[218:221], v[60:63]
	v_mfma_f32_16x16x32_bf16 v[56:59], v[202:205], v[218:221], v[56:59]
	v_mfma_f32_16x16x32_bf16 v[44:47], v[186:189], v[226:229], v[44:47]
	v_mfma_f32_16x16x32_bf16 v[40:43], v[202:205], v[226:229], v[40:43]
	v_mfma_f32_16x16x32_bf16 v[24:27], v[186:189], v[234:237], v[24:27]
	v_mfma_f32_16x16x32_bf16 v[28:31], v[202:205], v[234:237], v[28:31]
	v_mfma_f32_16x16x32_bf16 v[76:79], v[198:201], v[214:217], v[76:79]
	v_mfma_f32_16x16x32_bf16 v[72:75], v[206:209], v[214:217], v[72:75]
	v_mfma_f32_16x16x32_bf16 v[60:63], v[198:201], v[222:225], v[60:63]
	v_mfma_f32_16x16x32_bf16 v[56:59], v[206:209], v[222:225], v[56:59]
	v_mfma_f32_16x16x32_bf16 v[44:47], v[198:201], v[230:233], v[44:47]
	v_mfma_f32_16x16x32_bf16 v[40:43], v[206:209], v[230:233], v[40:43]
	v_mfma_f32_16x16x32_bf16 v[24:27], v[198:201], v[238:241], v[24:27]
	v_mfma_f32_16x16x32_bf16 v[28:31], v[206:209], v[238:241], v[28:31]
	s_barrier
	s_add_i32 s81, s81, 2
	s_cmp_eq_u32 s81, 2
	s_cselect_b32 s101, s32, s101
	s_add_u32 s38, s38, 0x100
	s_addc_u32 s39, s39, 0
	s_add_u32 s61, s61, 0x100
	s_addc_u32 s80, s80, 0
	s_cmp_gt_u32 s81, 13
	s_cbranch_scc0 .LBB0_206
	v_mov_b32_e32 v162, 0x500
	v_mov_b32_e32 v163, 0
	v_mov_b32_e32 v164, 0x4ff
	v_mov_b32_e32 v165, 0
	v_mov_b32_e32 v190, 0x358637bd
	v_mov_b32_e32 v191, 1
	v_mov_b32_e32 v192, 0x300
	v_mov_b32_e32 v193, 0x200
	s_and_b64 vcc, exec, s[22:23]
	s_cbranch_vccz .LBB0_209
	s_barrier
